# nt hint on final out stores (P11)
# baseline (speedup 1.0000x reference)
.LBB0_732:
	global_load_dwordx2 v[46:47], v[10:11], off offset:-1536
	global_load_dwordx2 v[48:49], v[10:11], off offset:-1024
	global_load_dwordx2 v[50:51], v[10:11], off offset:-512
	global_load_dwordx2 v[52:53], v[10:11], off
	global_load_dwordx4 v[22:25], v[12:13], off offset:-2048
	global_load_dwordx4 v[26:29], v[12:13], off offset:-1024
	global_load_dwordx4 v[4:7], v[12:13], off
	global_load_dwordx4 v[0:3], v[12:13], off offset:1024
	global_load_dwordx4 v[30:33], v[8:9], off
	global_load_dwordx4 v[34:37], v[8:9], off offset:1024
	global_load_dwordx4 v[38:41], v[8:9], off offset:2048
	global_load_dwordx4 v[42:45], v[8:9], off offset:3072
	s_add_i32 s2, s2, s8
	v_lshl_add_u64 v[10:11], v[10:11], 0, s[4:5]
	s_cmp_lt_i32 s2, 0x8000
	s_waitcnt vmcnt(0)
	v_lshlrev_b32_e32 v54, 16, v46
	v_and_b32_e32 v55, 0xffff0000, v46
	v_lshlrev_b32_e32 v46, 16, v47
	v_and_b32_e32 v47, 0xffff0000, v47
	v_lshlrev_b32_e32 v56, 16, v48
	v_and_b32_e32 v57, 0xffff0000, v48
	v_lshlrev_b32_e32 v48, 16, v49
	v_and_b32_e32 v49, 0xffff0000, v49
	v_lshlrev_b32_e32 v58, 16, v50
	v_and_b32_e32 v59, 0xffff0000, v50
	v_lshlrev_b32_e32 v50, 16, v51
	v_and_b32_e32 v51, 0xffff0000, v51
	v_mul_f32_e32 v62, v55, v55
	v_mul_f32_e32 v63, v47, v47
	v_mul_f32_e32 v64, v57, v57
	v_mul_f32_e32 v65, v49, v49
	v_lshlrev_b32_e32 v60, 16, v52
	v_and_b32_e32 v61, 0xffff0000, v52
	v_lshlrev_b32_e32 v52, 16, v53
	v_and_b32_e32 v53, 0xffff0000, v53
	v_mul_f32_e32 v66, v59, v59
	v_mul_f32_e32 v67, v51, v51
	v_fmac_f32_e32 v62, v54, v54
	v_fmac_f32_e32 v63, v46, v46
	v_fmac_f32_e32 v64, v56, v56
	v_fmac_f32_e32 v65, v48, v48
	v_mul_f32_e32 v68, v61, v61
	v_mul_f32_e32 v69, v53, v53
	v_fmac_f32_e32 v66, v58, v58
	v_fmac_f32_e32 v67, v50, v50
	v_add_f32_e32 v62, v62, v63
	v_add_f32_e32 v63, v64, v65
	v_fmac_f32_e32 v68, v60, v60
	v_fmac_f32_e32 v69, v52, v52
	v_add_f32_e32 v64, v66, v67
	v_add_f32_e32 v62, v62, v63
	v_add_f32_e32 v65, v68, v69
	v_add_f32_e32 v62, v62, v64
	v_add_f32_e32 v62, v62, v65
	ds_bpermute_b32 v63, v14, v62
	s_waitcnt lgkmcnt(0)
	v_add_f32_e32 v62, v62, v63
	ds_bpermute_b32 v63, v15, v62
	s_waitcnt lgkmcnt(0)
	v_add_f32_e32 v62, v62, v63
	ds_bpermute_b32 v63, v16, v62
	s_waitcnt lgkmcnt(0)
	v_add_f32_e32 v62, v62, v63
	ds_bpermute_b32 v63, v17, v62
	s_waitcnt lgkmcnt(0)
	v_add_f32_e32 v62, v62, v63
	ds_bpermute_b32 v63, v18, v62
	s_waitcnt lgkmcnt(0)
	v_add_f32_e32 v62, v62, v63
	ds_bpermute_b32 v63, v19, v62
	s_waitcnt lgkmcnt(0)
	v_add_f32_e32 v62, v62, v63
	v_fmamk_f32 v62, v62, 0x3a800000, v20
	v_mul_f32_e32 v63, 0x4f800000, v62
	v_cmp_gt_f32_e32 vcc, s3, v62
	s_nop 1
	v_cndmask_b32_e32 v62, v62, v63, vcc
	v_sqrt_f32_e32 v63, v62
	s_nop 0
	v_add_u32_e32 v64, -1, v63
	v_add_u32_e32 v65, 1, v63
	v_fma_f32 v66, -v64, v63, v62
	v_fma_f32 v67, -v65, v63, v62
	v_cmp_ge_f32_e64 s[0:1], 0, v66
	s_nop 1
	v_cndmask_b32_e64 v63, v63, v64, s[0:1]
	v_cmp_lt_f32_e64 s[0:1], 0, v67
	s_nop 1
	v_cndmask_b32_e64 v63, v63, v65, s[0:1]
	v_mul_f32_e32 v64, 0x37800000, v63
	v_cndmask_b32_e32 v63, v63, v64, vcc
	v_cmp_class_f32_e32 vcc, v62, v21
	s_nop 1
	v_cndmask_b32_e32 v62, v63, v62, vcc
	v_div_scale_f32 v63, s[0:1], v62, v62, 1.0
	v_rcp_f32_e32 v65, v63
	v_div_scale_f32 v64, vcc, 1.0, v62, 1.0
	v_fma_f32 v66, -v63, v65, 1.0
	v_fmac_f32_e32 v65, v66, v65
	v_mul_f32_e32 v66, v64, v65
	v_fma_f32 v67, -v63, v66, v64
	v_fmac_f32_e32 v66, v67, v65
	v_fma_f32 v63, -v63, v66, v64
	v_div_fmas_f32 v63, v63, v65, v66
	v_div_fixup_f32 v62, v63, v62, 1.0
	v_mul_f32_e32 v62, 0.5, v62
	v_pk_mul_f32 v[54:55], v[62:63], v[54:55] op_sel_hi:[0,1]
	v_pk_mul_f32 v[46:47], v[62:63], v[46:47] op_sel_hi:[0,1]
	v_pk_mul_f32 v[56:57], v[62:63], v[56:57] op_sel_hi:[0,1]
	v_pk_mul_f32 v[48:49], v[62:63], v[48:49] op_sel_hi:[0,1]
	v_pk_mul_f32 v[58:59], v[62:63], v[58:59] op_sel_hi:[0,1]
	v_pk_mul_f32 v[50:51], v[62:63], v[50:51] op_sel_hi:[0,1]
	v_pk_mul_f32 v[60:61], v[62:63], v[60:61] op_sel_hi:[0,1]
	v_pk_mul_f32 v[52:53], v[62:63], v[52:53] op_sel_hi:[0,1]
	v_pk_fma_f32 v[24:25], v[32:33], v[46:47], v[24:25]
	v_pk_fma_f32 v[22:23], v[30:31], v[54:55], v[22:23]
	v_pk_fma_f32 v[28:29], v[36:37], v[48:49], v[28:29]
	v_pk_fma_f32 v[26:27], v[34:35], v[56:57], v[26:27]
	v_pk_fma_f32 v[6:7], v[40:41], v[50:51], v[6:7]
	v_pk_fma_f32 v[4:5], v[38:39], v[58:59], v[4:5]
	v_pk_fma_f32 v[2:3], v[44:45], v[52:53], v[2:3]
	v_pk_fma_f32 v[0:1], v[42:43], v[60:61], v[0:1]
	global_store_dwordx4 v[12:13], v[22:25], off offset:-2048 nt
	global_store_dwordx4 v[12:13], v[26:29], off offset:-1024 nt
	global_store_dwordx4 v[12:13], v[4:7], off nt
	global_store_dwordx4 v[12:13], v[0:3], off offset:1024 nt
	v_lshl_add_u64 v[12:13], v[12:13], 0, s[6:7]
	s_cbranch_scc1 .LBB0_732
